# stack17 + norm1 extra rows batched + norm wave relabel variant 2: gw' = 4*vcu + (wave&3) + 1024*(wave>>2) (balance as before, four adjacent rows per half workgroup)
# baseline (speedup 1.0000x reference)
; #define GAS __attribute__((address_space(1)))
; __device__ __forceinline__ unsigned pk2(float lo, float hi) { return pg8::cvt_pk_bf16(lo, hi); }
; #define INP(k) (*(const float* const __attribute__((address_space(4)))*)(ka + 8 * (k)))
; __device__ __forceinline__ int launder_si(int v) { asm volatile("" : "+s"(v)); return v; }
; __device__ __forceinline__ void phase_norm(Frame& F, int l, int mode) {
;     ...
;     const int gw = launder_si(F.vcu * NWAVES + F.wave), NGW = F.G * NWAVES;
;     GAS bf16* XB = (GAS bf16*)out_; GAS bf16* XS = (GAS bf16*)(ws_ + WS_RKV); GAS bf16* HB = (GAS bf16*)(ws_ + WS_HB);
;     const float* gain = (mode == 0) ? INP(5) + (size_t)l * D : (mode == 1) ? INP(22) + (size_t)l * D : INP(25);
;     if (mode == 0 && gw < BS) {
;         const int j = gw; GAS v2u* o8 = (GAS v2u*)(HB + (size_t)(M + j) * D) + lane;
; #pragma unroll
;         for (int q = 0; q < 8; ++q) { const f32x4 s = *((const GAS f32x4*)(INP(3) + ((size_t)l * BS + j) * D) + lane + 64 * q); v2u w; w.x = pk2(s.x, s.y); w.y = pk2(s.z, s.w); o8[64 * q] = w; }
;     }
.LBB0_178:
	s_andn2_b64 vcc, exec, s[6:7]
	s_cbranch_vccnz .LBB0_256
	v_readlane_b32 s0, v254, 0
	v_readlane_b32 s1, v254, 1
	s_waitcnt lgkmcnt(0)
	s_load_dwordx4 s[8:11], s[0:1], 0xd0
	s_mov_b32 s18, s91
	s_mov_b64 s[6:7], s[0:1]
	s_waitcnt lgkmcnt(0)
	s_mov_b64 s[14:15], s[10:11]
	s_mov_b64 s[26:27], s[8:9]
	v_readlane_b32 s8, v254, 12
	s_and_b32 s98, s8, 3
	s_bfe_u32 s99, s8, 0x10002
	s_lshl_b32 s99, s99, 10
	s_lshr_b32 s8, s8, 3
	s_lshl_b32 s8, s8, 2
	s_add_i32 s8, s8, s98
	s_add_i32 s8, s8, s99
	v_mbcnt_lo_u32_b32 v2, -1, 0
	v_mbcnt_hi_u32_b32 v2, -1, v2
	s_load_dwordx2 s[10:11], s[6:7], 0x28
	s_add_u32 s0, s14, 0x1eb00000
	s_addc_u32 s1, s15, 0
	s_ashr_i32 s19, s18, 31
	s_cmp_gt_i32 s8, 15
	v_readlane_b32 s9, v254, 13
	s_cbranch_scc1 .LBB0_181
	s_load_dwordx2 s[16:17], s[6:7], 0x18
	s_ashr_i32 s9, s8, 31
	s_lshl_b64 s[12:13], s[8:9], 12
	s_add_u32 s12, s0, s12
	s_addc_u32 s13, s1, s13
	s_lshl_b64 s[20:21], s[18:19], 17
	s_waitcnt lgkmcnt(0)
	s_add_u32 s20, s16, s20
	s_addc_u32 s21, s17, s21
	s_lshl_b64 s[16:17], s[8:9], 13
	s_add_u32 s16, s20, s16
	v_ashrrev_i32_e32 v3, 31, v2
	s_addc_u32 s17, s21, s17
	v_lshl_add_u64 v[8:9], v[2:3], 4, s[16:17]
	global_load_dwordx4 v[14:17], v[8:9], off
	global_load_dwordx4 v[18:21], v[8:9], off offset:1024
	global_load_dwordx4 v[22:25], v[8:9], off offset:2048
	global_load_dwordx4 v[26:29], v[8:9], off offset:3072
	v_lshl_add_u64 v[10:11], v[2:3], 3, s[12:13]
	s_mov_b32 s9, 0x4400000
	v_add_co_u32_e32 v12, vcc, s9, v10
	s_mov_b64 s[12:13], 0x4400000
	s_nop 0
	v_addc_co_u32_e32 v13, vcc, 0, v11, vcc
	v_lshl_add_u64 v[10:11], v[10:11], 0, s[12:13]
	v_add_co_u32_e32 v8, vcc, s40, v8
	s_nop 1
	v_addc_co_u32_e32 v9, vcc, 0, v9, vcc
	global_load_dwordx4 v[30:33], v[8:9], off
	global_load_dwordx4 v[34:37], v[8:9], off offset:1024
	global_load_dwordx4 v[38:41], v[8:9], off offset:2048
	global_load_dwordx4 v[42:45], v[8:9], off offset:3072
	s_waitcnt vmcnt(7)
	v_cvt_pk_bf16_f32 v4, v14, v15
	v_cvt_pk_bf16_f32 v5, v16, v17
	global_store_dwordx2 v[12:13], v[4:5], off
	s_waitcnt vmcnt(7)
	v_cvt_pk_bf16_f32 v4, v18, v19
	v_cvt_pk_bf16_f32 v5, v20, v21
	global_store_dwordx2 v[10:11], v[4:5], off offset:512
	s_waitcnt vmcnt(7)
	v_cvt_pk_bf16_f32 v4, v22, v23
	v_cvt_pk_bf16_f32 v5, v24, v25
	global_store_dwordx2 v[10:11], v[4:5], off offset:1024
	s_waitcnt vmcnt(7)
	v_cvt_pk_bf16_f32 v4, v26, v27
	v_cvt_pk_bf16_f32 v5, v28, v29
	global_store_dwordx2 v[10:11], v[4:5], off offset:1536
	s_waitcnt vmcnt(7)
	v_cvt_pk_bf16_f32 v4, v30, v31
	v_cvt_pk_bf16_f32 v5, v32, v33
	global_store_dwordx2 v[10:11], v[4:5], off offset:2048
	s_waitcnt vmcnt(7)
	v_cvt_pk_bf16_f32 v4, v34, v35
	v_cvt_pk_bf16_f32 v5, v36, v37
	global_store_dwordx2 v[10:11], v[4:5], off offset:2560
	s_waitcnt vmcnt(7)
	v_cvt_pk_bf16_f32 v4, v38, v39
	v_cvt_pk_bf16_f32 v5, v40, v41
	global_store_dwordx2 v[10:11], v[4:5], off offset:3072
	s_waitcnt vmcnt(7)
	v_cvt_pk_bf16_f32 v4, v42, v43
	v_cvt_pk_bf16_f32 v5, v44, v45
	global_store_dwordx2 v[10:11], v[4:5], off offset:3584

; #define GAS __attribute__((address_space(1)))
; __device__ __forceinline__ unsigned pk2(float lo, float hi) { return pg8::cvt_pk_bf16(lo, hi); }
; #define INP(k) (*(const float* const __attribute__((address_space(4)))*)(ka + 8 * (k)))
; __device__ __forceinline__ int launder_si(int v) { asm volatile("" : "+s"(v)); return v; }
; __device__ __forceinline__ void phase_norm(Frame& F, int l, int mode) {
;     ...
;     const int gw = launder_si(F.vcu * NWAVES + F.wave), NGW = F.G * NWAVES;
;     GAS bf16* XB = (GAS bf16*)out_; GAS bf16* XS = (GAS bf16*)(ws_ + WS_RKV); GAS bf16* HB = (GAS bf16*)(ws_ + WS_HB);
;     const float* gain = (mode == 0) ? INP(5) + (size_t)l * D : (mode == 1) ? INP(22) + (size_t)l * D : INP(25);
;     if (mode == 0 && gw < BS) {
;         const int j = gw; GAS v2u* o8 = (GAS v2u*)(HB + (size_t)(M + j) * D) + lane;
; #pragma unroll
;         for (int q = 0; q < 8; ++q) { const f32x4 s = *((const GAS f32x4*)(INP(3) + ((size_t)l * BS + j) * D) + lane + 64 * q); v2u w; w.x = pk2(s.x, s.y); w.y = pk2(s.z, s.w); o8[64 * q] = w; }
;     }
;     f32x4 g[4][2];
; #pragma unroll
;     for (int q = 0; q < 4; ++q) { const GAS f32x4* gp = (const GAS f32x4*)(gain + q * 512 + lane * 8); g[q][0] = gp[0]; g[q][1] = gp[1]; }
;     const bool from_in = (mode == 0 && l == 0);
;     const GAS bf16* XR = (mode == 2) ? XS : XB;
;     GAS bf16* XW = (mode == 1 && l == NL - 1) ? XS : XB;
;     f32x4 nf[4][2]; v4u nb[4];
;     ...
;     if (gw < M) NORM_LOAD(gw);
.LBB0_1083:
	s_andn2_b64 vcc, exec, s[8:9]
	s_cbranch_vccnz .LBB0_1141
	v_readlane_b32 s0, v254, 0
	v_readlane_b32 s1, v254, 1
	s_mov_b32 s16, s91
	s_mov_b64 s[18:19], s[0:1]
	s_waitcnt lgkmcnt(0)
	s_load_dwordx4 s[8:11], s[0:1], 0xd0
	v_readlane_b32 s14, v254, 12
	s_and_b32 s98, s14, 3
	s_bfe_u32 s99, s14, 0x10002
	s_lshl_b32 s99, s99, 10
	s_lshr_b32 s14, s14, 3
	s_lshl_b32 s14, s14, 2
	s_add_i32 s14, s14, s98
	s_add_i32 s14, s14, s99
	v_mbcnt_lo_u32_b32 v0, -1, 0
	v_mbcnt_hi_u32_b32 v0, -1, v0
	s_waitcnt lgkmcnt(0)
	s_cmpk_gt_i32 s14, 0x43ff
	v_readlane_b32 s15, v254, 13
	s_cbranch_scc1 .LBB0_1093
	s_ashr_i32 s15, s14, 31
	s_lshl_b64 s[12:13], s[14:15], 12
	v_lshlrev_b32_e32 v2, 3, v0
	s_add_u32 s0, s8, s12
	v_ashrrev_i32_e32 v3, 31, v2
	s_addc_u32 s1, s9, s13
	v_lshlrev_b64 v[114:115], 1, v[2:3]
	v_lshl_add_u64 v[26:27], s[0:1], 0, v[114:115]
	s_add_u32 s15, s10, 0x3d5a0000
	s_load_dwordx2 s[0:1], s[18:19], 0xb0
	s_addc_u32 s17, s11, 0
	s_cmp_eq_u32 s16, 3
	s_cselect_b32 s19, s17, s9
	s_cselect_b32 s18, s15, s8
	s_ashr_i32 s17, s16, 31
	s_lshl_b64 s[16:17], s[16:17], 13
	s_waitcnt lgkmcnt(0)
	s_add_u32 s0, s0, s16
	s_addc_u32 s1, s1, s17
	v_lshl_add_u64 v[30:31], v[2:3], 2, s[0:1]
	s_mov_b64 s[0:1], 0x1800
	v_lshl_add_u64 v[2:3], v[30:31], 0, s[0:1]
	v_add_co_u32_e32 v10, vcc, s40, v30
	s_mov_b64 s[0:1], 0x1000
	s_nop 0
	v_addc_co_u32_e32 v11, vcc, 0, v31, vcc
	v_lshl_add_u64 v[14:15], v[30:31], 0, s[0:1]
	global_load_dwordx4 v[2:5], v[2:3], off offset:16
	s_nop 0
	global_load_dwordx4 v[6:9], v[10:11], off
	s_nop 0
	global_load_dwordx4 v[10:13], v[10:11], off offset:2048
	s_nop 0
	global_load_dwordx4 v[14:17], v[14:15], off offset:16
	s_nop 0
	global_load_dwordx4 v[18:21], v[30:31], off offset:2064
	global_load_dwordx4 v[22:25], v[30:31], off offset:2048
	global_load_dwordx4 v[54:57], v[26:27], off offset:2048
	global_load_dwordx4 v[50:53], v[26:27], off offset:3072
	global_load_dwordx4 v[62:65], v[26:27], off
	global_load_dwordx4 v[58:61], v[26:27], off offset:1024
	s_nop 0
	global_load_dwordx4 v[26:29], v[30:31], off offset:16
	s_nop 0
	global_load_dwordx4 v[30:33], v[30:31], off
	v_lshl_add_u64 v[34:35], s[10:11], 0, v[114:115]
	s_mov_b64 s[0:1], 0x43ba0000
	v_lshl_add_u64 v[116:117], v[34:35], 0, s[0:1]
	s_add_i32 s0, s44, s14
	s_ashr_i32 s1, s0, 31
	s_lshl_b64 s[0:1], s[0:1], 12
	s_add_u32 s8, s8, s0
	s_addc_u32 s9, s9, s1
	s_add_u32 s0, s10, s12
	s_addc_u32 s1, s11, s13
	s_add_u32 s10, s0, 0x1eb00000
	v_lshl_add_u64 v[118:119], s[18:19], 0, v[114:115]
	s_addc_u32 s11, s1, 0
	s_waitcnt vmcnt(0)
	v_mov_b64_e32 v[38:39], v[54:55]
	v_mov_b64_e32 v[34:35], v[50:51]
	v_mov_b64_e32 v[46:47], v[62:63]
	v_mov_b64_e32 v[42:43], v[58:59]
	v_mov_b64_e32 v[36:37], v[52:53]
	v_mov_b64_e32 v[40:41], v[56:57]
	v_mov_b64_e32 v[44:45], v[60:61]
	v_mov_b64_e32 v[48:49], v[64:65]
	s_branch .LBB0_1087

; #define GAS __attribute__((address_space(1)))
; __device__ __forceinline__ unsigned pk2(float lo, float hi) { return pg8::cvt_pk_bf16(lo, hi); }
; #define INP(k) (*(const float* const __attribute__((address_space(4)))*)(ka + 8 * (k)))
; __device__ __forceinline__ int launder_si(int v) { asm volatile("" : "+s"(v)); return v; }
; __device__ __forceinline__ void phase_norm(Frame& F, int l, int mode) {
;     ...
;     const int gw = launder_si(F.vcu * NWAVES + F.wave), NGW = F.G * NWAVES;
;     GAS bf16* XB = (GAS bf16*)out_; GAS bf16* XS = (GAS bf16*)(ws_ + WS_RKV); GAS bf16* HB = (GAS bf16*)(ws_ + WS_HB);
;     const float* gain = (mode == 0) ? INP(5) + (size_t)l * D : (mode == 1) ? INP(22) + (size_t)l * D : INP(25);
;     if (mode == 0 && gw < BS) {
;         const int j = gw; GAS v2u* o8 = (GAS v2u*)(HB + (size_t)(M + j) * D) + lane;
; #pragma unroll
;         for (int q = 0; q < 8; ++q) { const f32x4 s = *((const GAS f32x4*)(INP(3) + ((size_t)l * BS + j) * D) + lane + 64 * q); v2u w; w.x = pk2(s.x, s.y); w.y = pk2(s.z, s.w); o8[64 * q] = w; }
;     }
;     f32x4 g[4][2];
; #pragma unroll
;     for (int q = 0; q < 4; ++q) { const GAS f32x4* gp = (const GAS f32x4*)(gain + q * 512 + lane * 8); g[q][0] = gp[0]; g[q][1] = gp[1]; }
;     const bool from_in = (mode == 0 && l == 0);
;     const GAS bf16* XR = (mode == 2) ? XS : XB;
;     GAS bf16* XW = (mode == 1 && l == NL - 1) ? XS : XB;
;     f32x4 nf[4][2]; v4u nb[4];
;     ...
;     if (gw < M) NORM_LOAD(gw);
.LBB0_1290:
	s_cmp_lt_i32 s50, 50
	s_cselect_b64 s[0:1], -1, 0
	s_cmp_gt_i32 s51, 49
	s_cselect_b64 s[2:3], -1, 0
	s_and_b64 s[0:1], s[0:1], s[2:3]
	s_and_b64 vcc, exec, s[0:1]
	v_readlane_b32 s16, v254, 12
	s_and_b32 s98, s16, 3
	s_bfe_u32 s99, s16, 0x10002
	s_lshl_b32 s99, s99, 10
	s_lshr_b32 s16, s16, 3
	s_lshl_b32 s16, s16, 2
	s_add_i32 s16, s16, s98
	s_add_i32 s16, s16, s99
	v_readlane_b32 s17, v254, 13
	s_cbranch_vccz .LBB0_1298
	v_readlane_b32 s0, v254, 0
	v_readlane_b32 s1, v254, 1
	v_mbcnt_lo_u32_b32 v0, -1, 0
	v_mbcnt_hi_u32_b32 v0, -1, v0
	s_nop 0
	v_writelane_b32 v254, s0, 0
	s_nop 1
	v_writelane_b32 v254, s1, 1
	s_nop 0
	v_readlane_b32 s12, v254, 4
	v_readlane_b32 s13, v254, 5
	v_readlane_b32 s14, v254, 6
	v_readlane_b32 s15, v254, 7
	s_cmpk_gt_i32 s16, 0x43ff
	s_cbranch_scc1 .LBB0_1298
	v_readlane_b32 s2, v254, 0
	v_readlane_b32 s3, v254, 1
	s_add_u32 s4, s14, 0x3d5a0000
	s_load_dwordx2 s[2:3], s[2:3], 0xc8
	s_waitcnt lgkmcnt(0)
	s_addc_u32 s11, s15, 0
	s_ashr_i32 s17, s16, 31
	s_lshl_b64 s[0:1], s[16:17], 12
	v_lshlrev_b32_e32 v0, 3, v0
	s_add_u32 s0, s4, s0
	v_ashrrev_i32_e32 v1, 31, v0
	s_addc_u32 s1, s11, s1
	v_lshlrev_b64 v[32:33], 1, v[0:1]
	v_lshlrev_b64 v[36:37], 2, v[0:1]
	v_lshl_add_u64 v[34:35], s[0:1], 0, v[32:33]
	v_lshl_add_u64 v[38:39], s[2:3], 0, v[36:37]
	s_mov_b64 s[0:1], 0x1800
	s_movk_i32 s10, 0x1000
	v_lshl_add_u64 v[40:41], v[38:39], 0, s[0:1]
	v_add_co_u32_e32 v42, vcc, s10, v38
	s_mov_b64 s[2:3], 0x1000
	s_nop 0
	v_addc_co_u32_e32 v43, vcc, 0, v39, vcc
	v_lshl_add_u64 v[44:45], v[38:39], 0, s[2:3]
	global_load_dwordx4 v[0:3], v[40:41], off offset:16
	global_load_dwordx4 v[4:7], v[42:43], off
	global_load_dwordx4 v[8:11], v[38:39], off offset:2064
	global_load_dwordx4 v[12:15], v[38:39], off offset:2048
	global_load_dwordx4 v[16:19], v[38:39], off offset:16
	global_load_dwordx4 v[20:23], v[38:39], off
	global_load_dwordx4 v[52:55], v[34:35], off offset:2048
	global_load_dwordx4 v[48:51], v[34:35], off offset:3072
	global_load_dwordx4 v[60:63], v[34:35], off
	global_load_dwordx4 v[56:59], v[34:35], off offset:1024
	global_load_dwordx4 v[24:27], v[42:43], off offset:2048
	global_load_dwordx4 v[28:31], v[44:45], off offset:16
	s_mov_b64 s[6:7], 0x43ba0000
	v_lshl_add_u64 v[34:35], s[14:15], 0, v[32:33]
	v_lshl_add_u64 v[80:81], v[34:35], 0, s[6:7]
	s_lshl_b64 s[6:7], s[16:17], 13
	s_add_u32 s12, s12, s6
	s_addc_u32 s13, s13, s7
	s_add_i32 s14, s16, s44
	s_ashr_i32 s15, s14, 31
	s_lshl_b64 s[6:7], s[44:45], 13
	v_lshl_add_u64 v[82:83], s[12:13], 0, v[36:37]
	s_lshl_b64 s[12:13], s[14:15], 12
	s_add_u32 s12, s4, s12
	s_addc_u32 s13, s11, s13
	s_mov_b64 s[8:9], 0x800
	v_lshl_add_u64 v[32:33], s[12:13], 0, v[32:33]
	v_lshl_add_u64 v[84:85], v[32:33], 0, s[8:9]
	s_mov_b32 s5, 0
	v_mov_b32_e32 v134, 0x358637bd
	s_waitcnt vmcnt(0)
	v_mov_b64_e32 v[36:37], v[52:53]
	v_mov_b64_e32 v[32:33], v[48:49]
	v_mov_b64_e32 v[44:45], v[60:61]
	v_mov_b64_e32 v[40:41], v[56:57]
	v_mov_b64_e32 v[34:35], v[50:51]
	v_mov_b64_e32 v[38:39], v[54:55]
	v_mov_b64_e32 v[42:43], v[58:59]
	v_mov_b64_e32 v[46:47], v[62:63]
	s_branch .LBB0_1294
